# softmax row max/sum all-reduce via DPP (quad_perm, row_ror) instead of 32 serialized ds_bpermute round trips
# baseline (speedup 1.0000x reference)
; __device__ __forceinline__ void dsa_attend(const h16* PROJ, const unsigned short* IDX, const int* CNT, h16* MIXA, unsigned char* shm, unsigned* bar, unsigned xcc, unsigned xrank) {
;     ...
;             long qa8[4];
; #pragma unroll
;             for (int kk = 0; kk < 4; ++kk) {
;                 int w0 = __builtin_amdgcn_cvt_pk_fp8_f32((float)qa[kk][0], (float)qa[kk][1], 0, false); w0 = __builtin_amdgcn_cvt_pk_fp8_f32((float)qa[kk][2], (float)qa[kk][3], w0, true);
;                 int w1 = __builtin_amdgcn_cvt_pk_fp8_f32((float)qa[kk][4], (float)qa[kk][5], 0, false); w1 = __builtin_amdgcn_cvt_pk_fp8_f32((float)qa[kk][6], (float)qa[kk][7], w1, true);
;                 qa8[kk] = (long)(((unsigned long long)(unsigned)w1 << 32) | (unsigned long long)(unsigned)w0); }
;             f32x4 sacc[16];
;             const unsigned char* kbase8 = (const unsigned char*)(PROJ + O_KG) + (size_t)(b * 2 + g) * SEQ * 128 + 16 * fq;
;             {
;                 uint4 kf[16][2];
; #pragma unroll
;                 for (int e = 0; e < 16; ++e) { const int slot = 16 * e + fr; const int idx = (int)sel[qq * 256 + (slot < nsel ? slot : nsel - 1)];
;                     const unsigned char* krow = kbase8 + (size_t)idx * 128;
;                     kf[e][0] = *(const uint4*)krow; kf[e][1] = *(const uint4*)(krow + 64); }
.Lmy_att_full:
	s_waitcnt vmcnt(3)
	v_cvt_f32_f16_e32 v16, v12
	v_cvt_f32_f16_sdwa v12, v12 dst_sel:DWORD dst_unused:UNUSED_PAD src0_sel:WORD_1
	v_mov_b32_e32 v148, v163
	v_mov_b32_e32 v149, v163
	v_mov_b32_e32 v150, v163
	v_cvt_pk_fp8_f32 v148, v16, v12
	v_cvt_f32_f16_e32 v12, v13
	v_cvt_f32_f16_sdwa v13, v13 dst_sel:DWORD dst_unused:UNUSED_PAD src0_sel:WORD_1
	v_mov_b32_e32 v151, v163
	v_mov_b32_e32 v152, v163
	v_mov_b32_e32 v153, v163
	v_cvt_pk_fp8_f32 v148, v12, v13 op_sel:[0,0,1]
	v_cvt_f32_f16_e32 v12, v14
	v_cvt_f32_f16_sdwa v13, v14 dst_sel:DWORD dst_unused:UNUSED_PAD src0_sel:WORD_1
	v_mov_b32_e32 v154, v163
	v_mov_b32_e32 v155, v163
	s_max_i32 s50, s67, 1
	v_cvt_pk_fp8_f32 v149, v12, v13
	v_cvt_f32_f16_e32 v12, v15
	v_cvt_f32_f16_sdwa v13, v15 dst_sel:DWORD dst_unused:UNUSED_PAD src0_sel:WORD_1
	s_min_i32 s67, s50, 0x100
	s_add_i32 s70, s67, -1
	v_cvt_pk_fp8_f32 v149, v12, v13 op_sel:[0,0,1]
	s_waitcnt vmcnt(2)
	v_cvt_f32_f16_e32 v12, v8
	v_cvt_f32_f16_sdwa v8, v8 dst_sel:DWORD dst_unused:UNUSED_PAD src0_sel:WORD_1
	v_cvt_pk_fp8_f32 v150, v12, v8
	v_cvt_f32_f16_e32 v8, v9
	v_cvt_f32_f16_sdwa v9, v9 dst_sel:DWORD dst_unused:UNUSED_PAD src0_sel:WORD_1
	v_cvt_pk_fp8_f32 v150, v8, v9 op_sel:[0,0,1]
	v_cvt_f32_f16_e32 v8, v10
	v_cvt_f32_f16_sdwa v9, v10 dst_sel:DWORD dst_unused:UNUSED_PAD src0_sel:WORD_1
	v_cvt_pk_fp8_f32 v151, v8, v9
	v_cvt_f32_f16_e32 v8, v11
	v_cvt_f32_f16_sdwa v9, v11 dst_sel:DWORD dst_unused:UNUSED_PAD src0_sel:WORD_1
	s_waitcnt lgkmcnt(8)
	v_cvt_pk_fp8_f32 v151, v8, v9 op_sel:[0,0,1]
	s_waitcnt vmcnt(1)
	v_cvt_f32_f16_e32 v8, v0
	v_cvt_f32_f16_sdwa v0, v0 dst_sel:DWORD dst_unused:UNUSED_PAD src0_sel:WORD_1
	v_cvt_pk_fp8_f32 v152, v8, v0
	v_cvt_f32_f16_e32 v0, v1
	v_cvt_f32_f16_sdwa v1, v1 dst_sel:DWORD dst_unused:UNUSED_PAD src0_sel:WORD_1
	v_cvt_pk_fp8_f32 v152, v0, v1 op_sel:[0,0,1]
	v_cvt_f32_f16_e32 v0, v2
	v_cvt_f32_f16_sdwa v1, v2 dst_sel:DWORD dst_unused:UNUSED_PAD src0_sel:WORD_1
	v_cvt_pk_fp8_f32 v153, v0, v1
	v_cvt_f32_f16_e32 v0, v3
	v_cvt_f32_f16_sdwa v1, v3 dst_sel:DWORD dst_unused:UNUSED_PAD src0_sel:WORD_1
	v_cvt_pk_fp8_f32 v153, v0, v1 op_sel:[0,0,1]
	s_waitcnt vmcnt(0)
	v_cvt_f32_f16_e32 v0, v4
	v_cvt_f32_f16_sdwa v1, v4 dst_sel:DWORD dst_unused:UNUSED_PAD src0_sel:WORD_1
	v_cvt_pk_fp8_f32 v154, v0, v1
	v_cvt_f32_f16_e32 v0, v5
	v_cvt_f32_f16_sdwa v1, v5 dst_sel:DWORD dst_unused:UNUSED_PAD src0_sel:WORD_1
	v_cvt_pk_fp8_f32 v154, v0, v1 op_sel:[0,0,1]
	v_cvt_f32_f16_e32 v0, v6
	v_cvt_f32_f16_sdwa v1, v6 dst_sel:DWORD dst_unused:UNUSED_PAD src0_sel:WORD_1
	v_cvt_pk_fp8_f32 v155, v0, v1
	v_cvt_f32_f16_e32 v0, v7
	v_cvt_f32_f16_sdwa v1, v7 dst_sel:DWORD dst_unused:UNUSED_PAD src0_sel:WORD_1
	v_cvt_pk_fp8_f32 v155, v0, v1 op_sel:[0,0,1]
	ds_read_u16 v0, v240 offset:32768
	ds_read_u16 v8, v240 offset:32800
	ds_read_u16 v16, v240 offset:32832
	ds_read_u16 v24, v240 offset:32864
	ds_read_u16 v32, v240 offset:32896
	ds_read_u16 v40, v240 offset:32928
	ds_read_u16 v48, v240 offset:32960
	ds_read_u16 v56, v240 offset:32992
	ds_read_u16 v64, v240 offset:33024
	ds_read_u16 v72, v240 offset:33056
	ds_read_u16 v80, v240 offset:33088
	ds_read_u16 v84, v240 offset:33120
	ds_read_u16 v92, v240 offset:33152
	ds_read_u16 v100, v240 offset:33184
	ds_read_u16 v108, v240 offset:33216
	ds_read_u16 v120, v240 offset:33248
	s_waitcnt lgkmcnt(15)
	v_lshl_add_u32 v0, v0, 7, v242
	global_load_dwordx4 v[4:7], v0, s[98:99]
	s_nop 0
	global_load_dwordx4 v[0:3], v0, s[98:99] offset:64
	s_waitcnt lgkmcnt(14)
	v_lshl_add_u32 v8, v8, 7, v242
	global_load_dwordx4 v[12:15], v8, s[98:99]
	s_nop 0
	global_load_dwordx4 v[8:11], v8, s[98:99] offset:64
	s_waitcnt lgkmcnt(13)
	v_lshl_add_u32 v16, v16, 7, v242
	global_load_dwordx4 v[20:23], v16, s[98:99]
	s_nop 0
	global_load_dwordx4 v[16:19], v16, s[98:99] offset:64
	s_waitcnt lgkmcnt(12)
	v_lshl_add_u32 v24, v24, 7, v242
	global_load_dwordx4 v[28:31], v24, s[98:99]
	s_nop 0
	global_load_dwordx4 v[24:27], v24, s[98:99] offset:64
	s_waitcnt lgkmcnt(11)
	v_lshl_add_u32 v32, v32, 7, v242
	global_load_dwordx4 v[36:39], v32, s[98:99]
	s_nop 0
	global_load_dwordx4 v[32:35], v32, s[98:99] offset:64
	s_waitcnt lgkmcnt(10)
	v_lshl_add_u32 v40, v40, 7, v242
	global_load_dwordx4 v[44:47], v40, s[98:99]
	s_nop 0
	global_load_dwordx4 v[40:43], v40, s[98:99] offset:64
	s_waitcnt lgkmcnt(9)
	v_lshl_add_u32 v48, v48, 7, v242
	global_load_dwordx4 v[52:55], v48, s[98:99]
	s_nop 0
	global_load_dwordx4 v[48:51], v48, s[98:99] offset:64
	s_waitcnt lgkmcnt(8)
	v_lshl_add_u32 v56, v56, 7, v242
	global_load_dwordx4 v[60:63], v56, s[98:99]
	s_nop 0
	global_load_dwordx4 v[56:59], v56, s[98:99] offset:64
	s_waitcnt lgkmcnt(7)
	v_lshl_add_u32 v64, v64, 7, v242
	global_load_dwordx4 v[68:71], v64, s[98:99]
	s_nop 0
	global_load_dwordx4 v[64:67], v64, s[98:99] offset:64
	s_waitcnt lgkmcnt(6)
	v_lshl_add_u32 v72, v72, 7, v242
	global_load_dwordx4 v[76:79], v72, s[98:99]
	s_nop 0
	global_load_dwordx4 v[72:75], v72, s[98:99] offset:64
	s_waitcnt lgkmcnt(5)
	v_lshl_add_u32 v80, v80, 7, v242
	global_load_dwordx4 v[88:91], v80, s[98:99]
	s_nop 0
	global_load_dwordx4 v[80:83], v80, s[98:99] offset:64
	s_waitcnt lgkmcnt(4)
	v_lshl_add_u32 v84, v84, 7, v242
	global_load_dwordx4 v[96:99], v84, s[98:99]
	s_nop 0
	global_load_dwordx4 v[84:87], v84, s[98:99] offset:64
	s_waitcnt lgkmcnt(3)
	v_lshl_add_u32 v92, v92, 7, v242
	global_load_dwordx4 v[104:107], v92, s[98:99]
	s_nop 0
	global_load_dwordx4 v[92:95], v92, s[98:99] offset:64
	s_waitcnt lgkmcnt(2)
	v_lshl_add_u32 v100, v100, 7, v242
	global_load_dwordx4 v[112:115], v100, s[98:99]
	s_nop 0
	global_load_dwordx4 v[100:103], v100, s[98:99] offset:64
	s_waitcnt lgkmcnt(1)
; __device__ __forceinline__ void dsa_attend(const h16* PROJ, const unsigned short* IDX, const int* CNT, h16* MIXA, unsigned char* shm, unsigned* bar, unsigned xcc, unsigned xrank) {
;     ...
;                 for (int e = 0; e < 16; ++e) { const int slot = 16 * e + fr; const int idx = (int)sel[qq * 256 + (slot < nsel ? slot : nsel - 1)];
;                     const unsigned char* krow = kbase8 + (size_t)idx * 128;
;                     kf[e][0] = *(const uint4*)krow; kf[e][1] = *(const uint4*)(krow + 64); }
;                 __builtin_amdgcn_sched_barrier(0);
; #pragma unroll
;                 for (int e = 0; e < 16; ++e) {
;                     f32x4 a = (f32x4){0.f, 0.f, 0.f, 0.f};
; #pragma unroll
;                     for (int L = 0; L < 2; ++L) {
;                         const long k0 = (long)(((unsigned long long)kf[e][L].y << 32) | (unsigned long long)kf[e][L].x), k1 = (long)(((unsigned long long)kf[e][L].w << 32) | (unsigned long long)kf[e][L].z);
;                         a = __builtin_amdgcn_mfma_f32_16x16x32_fp8_fp8(qa8[2 * L], k0, a, 0, 0, 0); a = __builtin_amdgcn_mfma_f32_16x16x32_fp8_fp8(qa8[2 * L + 1], k1, a, 0, 0, 0); }
;                     if (16 * e + fr >= nsel) a = (f32x4){-1e30f, -1e30f, -1e30f, -1e30f};
;                     sacc[e] = a; }
	v_lshl_add_u32 v108, v108, 7, v242
	global_load_dwordx4 v[116:119], v108, s[98:99]
	s_nop 0
	global_load_dwordx4 v[108:111], v108, s[98:99] offset:64
	s_waitcnt lgkmcnt(0)
	v_lshl_add_u32 v120, v120, 7, v242
	global_load_dwordx4 v[124:127], v120, s[98:99]
	s_nop 0
	global_load_dwordx4 v[120:123], v120, s[98:99] offset:64
	s_waitcnt vmcnt(31)
	v_mfma_f32_16x16x32_fp8_fp8 v[156:159], v[148:149], v[4:5], 0
	v_cmp_gt_u32_e32 vcc, s50, v189
	v_mfma_f32_16x16x32_fp8_fp8 v[4:7], v[150:151], v[6:7], v[156:159]
	s_waitcnt vmcnt(30)
	v_mfma_f32_16x16x32_fp8_fp8 v[4:7], v[152:153], v[0:1], v[4:7]
	v_mfma_f32_16x16x32_fp8_fp8 v[4:7], v[154:155], v[2:3], v[4:7]
	s_waitcnt vmcnt(29)
	v_mfma_f32_16x16x32_fp8_fp8 v[0:3], v[148:149], v[12:13], 0
	v_mfma_f32_16x16x32_fp8_fp8 v[0:3], v[150:151], v[14:15], v[0:3]
	s_waitcnt vmcnt(28)
	v_mfma_f32_16x16x32_fp8_fp8 v[0:3], v[152:153], v[8:9], v[0:3]
	v_mfma_f32_16x16x32_fp8_fp8 v[8:11], v[154:155], v[10:11], v[0:3]
	s_waitcnt vmcnt(27)
	v_mfma_f32_16x16x32_fp8_fp8 v[0:3], v[148:149], v[20:21], 0
	v_mfma_f32_16x16x32_fp8_fp8 v[0:3], v[150:151], v[22:23], v[0:3]
	s_waitcnt vmcnt(26)
	v_mfma_f32_16x16x32_fp8_fp8 v[0:3], v[152:153], v[16:17], v[0:3]
	v_mfma_f32_16x16x32_fp8_fp8 v[12:15], v[154:155], v[18:19], v[0:3]
	s_waitcnt vmcnt(25)
	v_mfma_f32_16x16x32_fp8_fp8 v[0:3], v[148:149], v[28:29], 0
	v_mfma_f32_16x16x32_fp8_fp8 v[0:3], v[150:151], v[30:31], v[0:3]
	s_waitcnt vmcnt(24)
	v_mfma_f32_16x16x32_fp8_fp8 v[0:3], v[152:153], v[24:25], v[0:3]
	v_mfma_f32_16x16x32_fp8_fp8 v[16:19], v[154:155], v[26:27], v[0:3]
	s_waitcnt vmcnt(23)
	v_mfma_f32_16x16x32_fp8_fp8 v[0:3], v[148:149], v[36:37], 0
	v_mfma_f32_16x16x32_fp8_fp8 v[0:3], v[150:151], v[38:39], v[0:3]
	s_waitcnt vmcnt(22)
	v_mfma_f32_16x16x32_fp8_fp8 v[0:3], v[152:153], v[32:33], v[0:3]
	v_mfma_f32_16x16x32_fp8_fp8 v[20:23], v[154:155], v[34:35], v[0:3]
	s_waitcnt vmcnt(21)
	v_mfma_f32_16x16x32_fp8_fp8 v[0:3], v[148:149], v[44:45], 0
	v_mfma_f32_16x16x32_fp8_fp8 v[0:3], v[150:151], v[46:47], v[0:3]
	s_waitcnt vmcnt(20)
	v_mfma_f32_16x16x32_fp8_fp8 v[0:3], v[152:153], v[40:41], v[0:3]
	v_mfma_f32_16x16x32_fp8_fp8 v[24:27], v[154:155], v[42:43], v[0:3]
	s_waitcnt vmcnt(19)
	v_mfma_f32_16x16x32_fp8_fp8 v[0:3], v[148:149], v[52:53], 0
	v_mfma_f32_16x16x32_fp8_fp8 v[0:3], v[150:151], v[54:55], v[0:3]
	s_waitcnt vmcnt(18)
	v_mfma_f32_16x16x32_fp8_fp8 v[0:3], v[152:153], v[48:49], v[0:3]
	v_mfma_f32_16x16x32_fp8_fp8 v[28:31], v[154:155], v[50:51], v[0:3]
	s_waitcnt vmcnt(17)
	v_mfma_f32_16x16x32_fp8_fp8 v[0:3], v[148:149], v[60:61], 0
	v_mfma_f32_16x16x32_fp8_fp8 v[0:3], v[150:151], v[62:63], v[0:3]
	s_waitcnt vmcnt(16)
	v_mfma_f32_16x16x32_fp8_fp8 v[0:3], v[152:153], v[56:57], v[0:3]
	v_mfma_f32_16x16x32_fp8_fp8 v[32:35], v[154:155], v[58:59], v[0:3]
	s_waitcnt vmcnt(15)
	v_mfma_f32_16x16x32_fp8_fp8 v[0:3], v[148:149], v[68:69], 0
	v_mfma_f32_16x16x32_fp8_fp8 v[0:3], v[150:151], v[70:71], v[0:3]
	s_waitcnt vmcnt(14)
	v_mfma_f32_16x16x32_fp8_fp8 v[0:3], v[152:153], v[64:65], v[0:3]
	v_mfma_f32_16x16x32_fp8_fp8 v[36:39], v[154:155], v[66:67], v[0:3]
	s_waitcnt vmcnt(13)
	v_mfma_f32_16x16x32_fp8_fp8 v[0:3], v[148:149], v[76:77], 0
	v_mfma_f32_16x16x32_fp8_fp8 v[0:3], v[150:151], v[78:79], v[0:3]
	s_waitcnt vmcnt(11)
	v_mfma_f32_16x16x32_fp8_fp8 v[44:47], v[148:149], v[88:89], 0
	s_waitcnt vmcnt(9)
	v_mfma_f32_16x16x32_fp8_fp8 v[48:51], v[148:149], v[96:97], 0
	v_mfma_f32_16x16x32_fp8_fp8 v[0:3], v[152:153], v[72:73], v[0:3]
	s_waitcnt vmcnt(7)
	v_mfma_f32_16x16x32_fp8_fp8 v[52:55], v[148:149], v[104:105], 0
	s_waitcnt vmcnt(5)
	v_mfma_f32_16x16x32_fp8_fp8 v[56:59], v[148:149], v[112:113], 0
	v_mfma_f32_16x16x32_fp8_fp8 v[44:47], v[150:151], v[90:91], v[44:47]
	s_waitcnt vmcnt(3)
	v_mfma_f32_16x16x32_fp8_fp8 v[60:63], v[148:149], v[116:117], 0
	v_mfma_f32_16x16x32_fp8_fp8 v[48:51], v[150:151], v[98:99], v[48:51]
	v_mfma_f32_16x16x32_fp8_fp8 v[40:43], v[154:155], v[74:75], v[0:3]
	s_nop 2
	v_cndmask_b32_e32 v2, v219, v7, vcc
	v_cndmask_b32_e32 v3, v219, v6, vcc
	v_cndmask_b32_e32 v1, v219, v5, vcc
	v_cndmask_b32_e32 v0, v219, v4, vcc
	v_cmp_gt_u32_e32 vcc, s67, v194
	v_mfma_f32_16x16x32_fp8_fp8 v[52:55], v[150:151], v[106:107], v[52:55]
	s_nop 0
	v_cndmask_b32_e32 v7, v219, v11, vcc
	v_cndmask_b32_e32 v6, v219, v10, vcc
	v_cndmask_b32_e32 v9, v219, v9, vcc
	v_cndmask_b32_e32 v8, v219, v8, vcc
	v_cmp_gt_u32_e32 vcc, s67, v195
	v_mfma_f32_16x16x32_fp8_fp8 v[56:59], v[150:151], v[114:115], v[56:59]
	s_nop 0
	v_cndmask_b32_e32 v11, v219, v15, vcc
	v_cndmask_b32_e32 v10, v219, v14, vcc
	v_mfma_f32_16x16x32_fp8_fp8 v[44:47], v[152:153], v[80:81], v[44:47]
	v_cndmask_b32_e32 v69, v219, v13, vcc
	v_cndmask_b32_e32 v12, v219, v12, vcc
	v_cmp_gt_u32_e32 vcc, s67, v196
	v_mfma_f32_16x16x32_fp8_fp8 v[60:63], v[150:151], v[118:119], v[60:63]
	s_nop 0
	v_cndmask_b32_e32 v15, v219, v19, vcc
	v_cndmask_b32_e32 v14, v219, v18, vcc
	s_waitcnt vmcnt(1)
; __device__ __forceinline__ void dsa_attend(const h16* PROJ, const unsigned short* IDX, const int* CNT, h16* MIXA, unsigned char* shm, unsigned* bar, unsigned xcc, unsigned xrank) {
;     ...
;                     if (16 * e + fr >= nsel) a = (f32x4){-1e30f, -1e30f, -1e30f, -1e30f};
;                     sacc[e] = a; }
;                 __builtin_amdgcn_sched_barrier(0);
;             }
;             f32x4 mx = sacc[0];
; #pragma unroll
;             for (int jt = 1; jt < 16; ++jt)
; #pragma unroll
;                 for (int i = 0; i < 4; ++i) mx[i] = fmaxf(mx[i], sacc[jt][i]);
; #pragma unroll
;             for (int o = 1; o < 16; o <<= 1)
; #pragma unroll
;                 for (int i = 0; i < 4; ++i) mx[i] = fmaxf(mx[i], __shfl_xor(mx[i], o));
	v_mfma_f32_16x16x32_fp8_fp8 v[64:67], v[148:149], v[124:125], 0
	v_cndmask_b32_e32 v13, v219, v17, vcc
	v_cndmask_b32_e32 v70, v219, v16, vcc
	v_cmp_gt_u32_e32 vcc, s67, v197
	v_mfma_f32_16x16x32_fp8_fp8 v[48:51], v[152:153], v[84:85], v[48:51]
	s_nop 0
	v_cndmask_b32_e32 v19, v219, v23, vcc
	v_cndmask_b32_e32 v18, v219, v22, vcc
	v_cndmask_b32_e32 v17, v219, v21, vcc
	v_cndmask_b32_e32 v16, v219, v20, vcc
	v_cmp_gt_u32_e32 vcc, s67, v198
	v_mfma_f32_16x16x32_fp8_fp8 v[52:55], v[152:153], v[92:93], v[52:55]
	s_nop 0
	v_cndmask_b32_e32 v23, v219, v27, vcc
	v_cndmask_b32_e32 v22, v219, v26, vcc
	v_cndmask_b32_e32 v21, v219, v25, vcc
	v_cndmask_b32_e32 v20, v219, v24, vcc
	v_cmp_gt_u32_e32 vcc, s67, v199
	v_mfma_f32_16x16x32_fp8_fp8 v[56:59], v[152:153], v[100:101], v[56:59]
	s_nop 0
	v_cndmask_b32_e32 v27, v219, v31, vcc
	v_cndmask_b32_e32 v26, v219, v30, vcc
	v_mfma_f32_16x16x32_fp8_fp8 v[44:47], v[154:155], v[82:83], v[44:47]
	v_cndmask_b32_e32 v25, v219, v29, vcc
	v_cndmask_b32_e32 v24, v219, v28, vcc
	v_cmp_gt_u32_e32 vcc, s67, v200
	v_mfma_f32_16x16x32_fp8_fp8 v[60:63], v[152:153], v[108:109], v[60:63]
	s_nop 0
	v_cndmask_b32_e32 v31, v219, v35, vcc
	v_cndmask_b32_e32 v30, v219, v34, vcc
	v_mfma_f32_16x16x32_fp8_fp8 v[64:67], v[150:151], v[126:127], v[64:67]
	v_cndmask_b32_e32 v29, v219, v33, vcc
	v_cndmask_b32_e32 v28, v219, v32, vcc
	v_cmp_gt_u32_e32 vcc, s67, v201
	v_mfma_f32_16x16x32_fp8_fp8 v[48:51], v[154:155], v[86:87], v[48:51]
	s_nop 0
	v_cndmask_b32_e32 v35, v219, v39, vcc
	v_cndmask_b32_e32 v34, v219, v38, vcc
	v_mfma_f32_16x16x32_fp8_fp8 v[52:55], v[154:155], v[94:95], v[52:55]
	v_cndmask_b32_e32 v33, v219, v37, vcc
	v_cndmask_b32_e32 v32, v219, v36, vcc
	v_cmp_gt_u32_e32 vcc, s67, v202
	v_mfma_f32_16x16x32_fp8_fp8 v[56:59], v[154:155], v[102:103], v[56:59]
	s_nop 0
	v_cndmask_b32_e32 v39, v219, v43, vcc
	v_cndmask_b32_e32 v38, v219, v42, vcc
	v_cndmask_b32_e32 v37, v219, v41, vcc
	v_cndmask_b32_e32 v36, v219, v40, vcc
	v_cmp_gt_u32_e32 vcc, s67, v203
	v_mfma_f32_16x16x32_fp8_fp8 v[60:63], v[154:155], v[110:111], v[60:63]
	s_nop 0
	v_cndmask_b32_e32 v43, v219, v47, vcc
	v_cndmask_b32_e32 v42, v219, v46, vcc
	v_cndmask_b32_e32 v41, v219, v45, vcc
	v_cndmask_b32_e32 v40, v219, v44, vcc
	v_cmp_gt_u32_e32 vcc, s67, v204
	s_waitcnt vmcnt(0)
	v_mfma_f32_16x16x32_fp8_fp8 v[64:67], v[152:153], v[120:121], v[64:67]
	v_cndmask_b32_e32 v47, v219, v51, vcc
	v_cndmask_b32_e32 v46, v219, v50, vcc
	v_cndmask_b32_e32 v45, v219, v49, vcc
	v_cndmask_b32_e32 v44, v219, v48, vcc
	v_cmp_gt_u32_e32 vcc, s67, v205
	s_nop 1
	v_cndmask_b32_e32 v51, v219, v55, vcc
	v_cndmask_b32_e32 v50, v219, v54, vcc
	v_cndmask_b32_e32 v49, v219, v53, vcc
	v_cndmask_b32_e32 v48, v219, v52, vcc
	v_cmp_gt_u32_e32 vcc, s67, v206
	s_nop 1
	v_cndmask_b32_e32 v55, v219, v59, vcc
	v_cndmask_b32_e32 v54, v219, v58, vcc
	v_cndmask_b32_e32 v53, v219, v57, vcc
	v_cndmask_b32_e32 v52, v219, v56, vcc
	v_cmp_gt_u32_e32 vcc, s67, v207
	s_nop 1
	v_cndmask_b32_e32 v59, v219, v63, vcc
	v_cndmask_b32_e32 v58, v219, v62, vcc
	v_cndmask_b32_e32 v57, v219, v61, vcc
	v_cndmask_b32_e32 v56, v219, v60, vcc
	v_mfma_f32_16x16x32_fp8_fp8 v[60:63], v[154:155], v[122:123], v[64:67]
	v_cmp_gt_u32_e32 vcc, s67, v208
	s_nop 6
	v_cndmask_b32_e32 v63, v219, v63, vcc
	v_cndmask_b32_e32 v62, v219, v62, vcc
	v_cndmask_b32_e32 v61, v219, v61, vcc
	v_cndmask_b32_e32 v60, v219, v60, vcc
	v_max_f32_e32 v4, v8, v8
	v_max_f32_e32 v5, v0, v0
	v_max_f32_e32 v4, v5, v4
	v_max_f32_e32 v5, v9, v9
	v_max_f32_e32 v64, v1, v1
	v_max_f32_e32 v5, v64, v5
	v_max_f32_e32 v64, v6, v6
	v_max_f32_e32 v65, v3, v3
	v_max3_f32 v4, v4, v12, v70
	v_max_f32_e32 v64, v65, v64
	v_max_f32_e32 v65, v7, v7
	v_max_f32_e32 v66, v2, v2
	v_max3_f32 v4, v4, v16, v20
	v_max_f32_e32 v65, v66, v65
	v_max3_f32 v4, v4, v24, v28
	v_and_b32_e32 v66, 64, v216
	v_max3_f32 v4, v4, v32, v36
	v_add_u32_e32 v224, 64, v66
	v_xor_b32_e32 v66, 1, v216
	v_max3_f32 v4, v4, v40, v44
	v_cmp_lt_i32_e32 vcc, v66, v224
	v_max3_f32 v4, v4, v48, v52
	v_max3_f32 v5, v5, v69, v13
	v_cndmask_b32_e32 v66, v216, v66, vcc
	v_max3_f32 v4, v4, v56, v60
	v_lshlrev_b32_e32 v66, 2, v66
	v_max3_f32 v5, v5, v17, v21
	s_nop 1
	v_mov_b32_dpp v67, v4 quad_perm:[1,0,3,2] row_mask:0xf bank_mask:0xf
	v_max3_f32 v5, v5, v25, v29
	v_max3_f32 v5, v5, v33, v37
	v_max3_f32 v5, v5, v41, v45
	v_max3_f32 v5, v5, v49, v53
	v_max3_f32 v64, v64, v10, v14
	v_max3_f32 v5, v5, v57, v61
	s_waitcnt lgkmcnt(0)
	v_max_f32_e32 v67, v67, v67
	v_max3_f32 v64, v64, v18, v22
	v_max_f32_e32 v4, v4, v67
	s_nop 1
	v_mov_b32_dpp v67, v5 quad_perm:[1,0,3,2] row_mask:0xf bank_mask:0xf
	v_max3_f32 v64, v64, v26, v30
	v_max3_f32 v64, v64, v34, v38
	v_max3_f32 v64, v64, v42, v46
	v_max3_f32 v64, v64, v50, v54
	v_max3_f32 v65, v65, v11, v15
	v_max3_f32 v64, v64, v58, v62
	s_waitcnt lgkmcnt(0)
	v_max_f32_e32 v67, v67, v67
	v_max3_f32 v65, v65, v19, v23
	v_max_f32_e32 v5, v5, v67
	s_nop 1
	v_mov_b32_dpp v67, v64 quad_perm:[1,0,3,2] row_mask:0xf bank_mask:0xf
	v_max3_f32 v65, v65, v27, v31
	v_max3_f32 v65, v65, v35, v39
	v_max3_f32 v65, v65, v43, v47
	v_max3_f32 v65, v65, v51, v55
	v_max3_f32 v65, v65, v59, v63
	s_waitcnt lgkmcnt(0)
	v_max_f32_e32 v67, v67, v67
	v_max_f32_e32 v64, v64, v67
	s_nop 1
	v_mov_b32_dpp v67, v65 quad_perm:[1,0,3,2] row_mask:0xf bank_mask:0xf
	s_waitcnt lgkmcnt(0)
	v_max_f32_e32 v67, v67, v67
	v_max_f32_e32 v65, v65, v67
	v_xor_b32_e32 v67, 2, v216
	v_cmp_lt_i32_e32 vcc, v67, v224
	s_nop 1
	v_cndmask_b32_e32 v67, v216, v67, vcc
	v_lshlrev_b32_e32 v67, 2, v67
	s_nop 1
	v_mov_b32_dpp v68, v4 quad_perm:[2,3,0,1] row_mask:0xf bank_mask:0xf
	s_waitcnt lgkmcnt(0)
; __device__ __forceinline__ void dsa_attend(const h16* PROJ, const unsigned short* IDX, const int* CNT, h16* MIXA, unsigned char* shm, unsigned* bar, unsigned xcc, unsigned xrank) {
;     ...
;             for (int o = 1; o < 16; o <<= 1)
; #pragma unroll
;                 for (int i = 0; i < 4; ++i) mx[i] = fmaxf(mx[i], __shfl_xor(mx[i], o));
;             f32x4 sm = (f32x4){0.f, 0.f, 0.f, 0.f};
;             const float sc = 0.08838834764831845f;
; #pragma unroll
;             for (int jt = 0; jt < 16; ++jt)
; #pragma unroll
;                 for (int i = 0; i < 4; ++i) { const float e = __expf((sacc[jt][i] - mx[i]) * sc); sacc[jt][i] = e; sm[i] += e; }
; #pragma unroll
;             for (int o = 1; o < 16; o <<= 1)
; #pragma unroll
;                 for (int i = 0; i < 4; ++i) sm[i] += __shfl_xor(sm[i], o);
	v_max_f32_e32 v68, v68, v68
	v_max_f32_e32 v4, v4, v68
	s_nop 1
	v_mov_b32_dpp v68, v5 quad_perm:[2,3,0,1] row_mask:0xf bank_mask:0xf
	s_waitcnt lgkmcnt(0)
	v_max_f32_e32 v68, v68, v68
	v_max_f32_e32 v5, v5, v68
	s_nop 1
	v_mov_b32_dpp v68, v64 quad_perm:[2,3,0,1] row_mask:0xf bank_mask:0xf
	s_waitcnt lgkmcnt(0)
	v_max_f32_e32 v68, v68, v68
	v_max_f32_e32 v64, v64, v68
	s_nop 1
	v_mov_b32_dpp v68, v65 quad_perm:[2,3,0,1] row_mask:0xf bank_mask:0xf
	s_waitcnt lgkmcnt(0)
	v_max_f32_e32 v68, v68, v68
	v_max_f32_e32 v65, v65, v68
	v_xor_b32_e32 v68, 4, v216
	v_cmp_lt_i32_e32 vcc, v68, v224
	s_nop 1
	v_cndmask_b32_e32 v68, v216, v68, vcc
	v_lshlrev_b32_e32 v68, 2, v68
	s_nop 1
	v_mov_b32_dpp v71, v4 row_ror:4 row_mask:0xf bank_mask:0xf
	s_waitcnt lgkmcnt(0)
	v_max_f32_e32 v71, v71, v71
	v_max_f32_e32 v4, v4, v71
	s_nop 1
	v_mov_b32_dpp v71, v5 row_ror:4 row_mask:0xf bank_mask:0xf
	s_waitcnt lgkmcnt(0)
	v_max_f32_e32 v71, v71, v71
	v_max_f32_e32 v5, v5, v71
	s_nop 1
	v_mov_b32_dpp v71, v64 row_ror:4 row_mask:0xf bank_mask:0xf
	s_waitcnt lgkmcnt(0)
	v_max_f32_e32 v71, v71, v71
	v_max_f32_e32 v64, v64, v71
	s_nop 1
	v_mov_b32_dpp v71, v65 row_ror:4 row_mask:0xf bank_mask:0xf
	s_waitcnt lgkmcnt(0)
	v_max_f32_e32 v71, v71, v71
	v_max_f32_e32 v65, v65, v71
	v_xor_b32_e32 v71, 8, v216
	v_cmp_lt_i32_e32 vcc, v71, v224
	s_nop 1
	v_cndmask_b32_e32 v71, v216, v71, vcc
	v_lshlrev_b32_e32 v223, 2, v71
	s_nop 1
	v_mov_b32_dpp v71, v4 row_ror:8 row_mask:0xf bank_mask:0xf
	s_waitcnt lgkmcnt(0)
	v_max_f32_e32 v71, v71, v71
	v_max_f32_e32 v72, v4, v71
	s_nop 1
	v_mov_b32_dpp v4, v5 row_ror:8 row_mask:0xf bank_mask:0xf
	v_mul_f32_e32 v236, 0xbe0293ee, v72
	v_fma_f32 v0, v0, v244, v236
	v_exp_f32_e32 v0, v0
	s_waitcnt lgkmcnt(0)
	v_max_f32_e32 v4, v4, v4
	v_max_f32_e32 v73, v5, v4
	s_nop 1
	v_mov_b32_dpp v4, v64 row_ror:8 row_mask:0xf bank_mask:0xf
	v_mul_f32_e32 v237, 0xbe0293ee, v73
	v_fma_f32 v1, v1, v244, v237
	v_exp_f32_e32 v1, v1
	s_waitcnt lgkmcnt(0)
	v_max_f32_e32 v4, v4, v4
	v_max_f32_e32 v74, v64, v4
	s_nop 1
	v_mov_b32_dpp v4, v65 row_ror:8 row_mask:0xf bank_mask:0xf
	v_mul_f32_e32 v238, 0xbe0293ee, v74
	v_fma_f32 v3, v3, v244, v238
	v_fma_f32 v13, v13, v244, v237
	s_waitcnt lgkmcnt(0)
	v_max_f32_e32 v4, v4, v4
	v_max_f32_e32 v75, v65, v4
	v_mul_f32_e32 v239, 0xbe0293ee, v75
	v_fma_f32 v2, v2, v244, v239
	v_exp_f32_e32 v4, v3
	v_exp_f32_e32 v5, v2
	v_fma_f32 v2, v8, v244, v236
	v_fma_f32 v3, v9, v244, v237
	v_fma_f32 v8, v12, v244, v236
	v_fma_f32 v9, v69, v244, v237
	v_fma_f32 v12, v70, v244, v236
	v_exp_f32_e32 v2, v2
	v_exp_f32_e32 v3, v3
	v_fma_f32 v16, v16, v244, v236
	v_fma_f32 v17, v17, v244, v237
	v_exp_f32_e32 v8, v8
	v_exp_f32_e32 v9, v9
	v_fma_f32 v20, v20, v244, v236
	v_fma_f32 v21, v21, v244, v237
	v_exp_f32_e32 v12, v12
	v_exp_f32_e32 v13, v13
	v_fma_f32 v24, v24, v244, v236
	v_fma_f32 v25, v25, v244, v237
	v_exp_f32_e32 v16, v16
	v_exp_f32_e32 v17, v17
	v_fma_f32 v28, v28, v244, v236
	v_fma_f32 v29, v29, v244, v237
	v_pk_add_f32 v[64:65], v[0:1], 0 op_sel_hi:[1,0]
	v_exp_f32_e32 v20, v20
	v_exp_f32_e32 v21, v21
	v_fma_f32 v32, v32, v244, v236
	v_fma_f32 v33, v33, v244, v237
	v_pk_add_f32 v[64:65], v[2:3], v[64:65]
	v_exp_f32_e32 v24, v24
	v_exp_f32_e32 v25, v25
	v_fma_f32 v36, v36, v244, v236
	v_fma_f32 v37, v37, v244, v237
	v_pk_add_f32 v[64:65], v[8:9], v[64:65]
	v_exp_f32_e32 v28, v28
	v_exp_f32_e32 v29, v29
	v_pk_add_f32 v[64:65], v[12:13], v[64:65]
	v_fma_f32 v40, v40, v244, v236
	v_fma_f32 v41, v41, v244, v237
	v_exp_f32_e32 v32, v32
	v_exp_f32_e32 v33, v33
	v_pk_add_f32 v[64:65], v[16:17], v[64:65]
	v_fma_f32 v44, v44, v244, v236
	v_fma_f32 v45, v45, v244, v237
	v_exp_f32_e32 v36, v36
	v_exp_f32_e32 v37, v37
	v_pk_add_f32 v[64:65], v[20:21], v[64:65]
	v_fma_f32 v48, v48, v244, v236
	v_fma_f32 v49, v49, v244, v237
	v_pk_add_f32 v[64:65], v[24:25], v[64:65]
	v_exp_f32_e32 v40, v40
	v_exp_f32_e32 v41, v41
	v_fma_f32 v52, v52, v244, v236
	v_fma_f32 v53, v53, v244, v237
	v_pk_add_f32 v[64:65], v[28:29], v[64:65]
	v_exp_f32_e32 v44, v44
	v_exp_f32_e32 v45, v45
	v_fma_f32 v56, v56, v244, v236
	v_fma_f32 v57, v57, v244, v237
	v_pk_add_f32 v[64:65], v[32:33], v[64:65]
	v_exp_f32_e32 v48, v48
	v_exp_f32_e32 v49, v49
	v_fma_f32 v60, v60, v244, v236
	v_fma_f32 v61, v61, v244, v237
	v_pk_add_f32 v[64:65], v[36:37], v[64:65]
	v_exp_f32_e32 v52, v52
	v_exp_f32_e32 v53, v53
	v_exp_f32_e32 v56, v56
	v_exp_f32_e32 v57, v57
	v_pk_add_f32 v[64:65], v[40:41], v[64:65]
	v_fma_f32 v6, v6, v244, v238
	v_fma_f32 v7, v7, v244, v239
	v_exp_f32_e32 v60, v60
	v_exp_f32_e32 v61, v61
	v_pk_add_f32 v[64:65], v[44:45], v[64:65]
	v_fma_f32 v10, v10, v244, v238
	v_fma_f32 v11, v11, v244, v239
	v_pk_add_f32 v[64:65], v[48:49], v[64:65]
	v_fma_f32 v14, v14, v244, v238
	v_fma_f32 v15, v15, v244, v239
	v_pk_add_f32 v[64:65], v[52:53], v[64:65]
	v_exp_f32_e32 v6, v6
	v_exp_f32_e32 v7, v7
	v_fma_f32 v18, v18, v244, v238
	v_fma_f32 v19, v19, v244, v239
	v_pk_add_f32 v[64:65], v[56:57], v[64:65]
	v_exp_f32_e32 v10, v10
	v_exp_f32_e32 v11, v11
	v_fma_f32 v22, v22, v244, v238
	v_fma_f32 v23, v23, v244, v239
	v_pk_add_f32 v[64:65], v[60:61], v[64:65]
	v_exp_f32_e32 v14, v14
	v_exp_f32_e32 v15, v15
	v_fma_f32 v26, v26, v244, v238
	v_fma_f32 v27, v27, v244, v239
	s_nop 1
	v_mov_b32_dpp v72, v64 quad_perm:[1,0,3,2] row_mask:0xf bank_mask:0xf
	s_nop 1
	v_mov_b32_dpp v73, v65 quad_perm:[1,0,3,2] row_mask:0xf bank_mask:0xf
	v_exp_f32_e32 v18, v18
	v_exp_f32_e32 v19, v19
	v_fma_f32 v30, v30, v244, v238
	v_fma_f32 v31, v31, v244, v239
	v_pk_add_f32 v[70:71], v[4:5], 0 op_sel_hi:[1,0]
	v_exp_f32_e32 v22, v22
	v_exp_f32_e32 v23, v23
	v_fma_f32 v34, v34, v244, v238
	v_fma_f32 v35, v35, v244, v239
	v_pk_add_f32 v[70:71], v[6:7], v[70:71]
	v_exp_f32_e32 v26, v26
	v_exp_f32_e32 v27, v27
	v_fma_f32 v38, v38, v244, v238
	v_fma_f32 v39, v39, v244, v239
	v_pk_add_f32 v[70:71], v[10:11], v[70:71]
	v_exp_f32_e32 v30, v30
	v_exp_f32_e32 v31, v31
	v_pk_add_f32 v[70:71], v[14:15], v[70:71]
	v_fma_f32 v42, v42, v244, v238
	v_fma_f32 v43, v43, v244, v239
	v_exp_f32_e32 v34, v34
	v_exp_f32_e32 v35, v35
	v_pk_add_f32 v[70:71], v[18:19], v[70:71]
	v_fma_f32 v46, v46, v244, v238
	v_fma_f32 v47, v47, v244, v239
	s_waitcnt lgkmcnt(0)
; __device__ __forceinline__ void dsa_attend(const h16* PROJ, const unsigned short* IDX, const int* CNT, h16* MIXA, unsigned char* shm, unsigned* bar, unsigned xcc, unsigned xrank) {
;     ...
;                 for (int i = 0; i < 4; ++i) { const float e = __expf((sacc[jt][i] - mx[i]) * sc); sacc[jt][i] = e; sm[i] += e; }
; #pragma unroll
;             for (int o = 1; o < 16; o <<= 1)
; #pragma unroll
;                 for (int i = 0; i < 4; ++i) sm[i] += __shfl_xor(sm[i], o);
;             f32x4 inv;
; #pragma unroll
;             for (int i = 0; i < 4; ++i) inv[i] = 1.f / sm[i];
;             if (fq == 0) {
; #pragma unroll
;                 for (int jt = 0; jt < 16; ++jt) *(f32x4*)(Pl + ((size_t)wid * 256 + 16 * jt + fr) * 4) = sacc[jt] * inv;
;             }
	v_pk_add_f32 v[64:65], v[64:65], v[72:73]
	v_exp_f32_e32 v38, v38
	v_exp_f32_e32 v39, v39
	v_pk_add_f32 v[70:71], v[22:23], v[70:71]
	v_fma_f32 v50, v50, v244, v238
	v_fma_f32 v51, v51, v244, v239
	s_nop 1
	v_mov_b32_dpp v72, v64 quad_perm:[2,3,0,1] row_mask:0xf bank_mask:0xf
	s_nop 1
	v_mov_b32_dpp v73, v65 quad_perm:[2,3,0,1] row_mask:0xf bank_mask:0xf
	v_pk_add_f32 v[70:71], v[26:27], v[70:71]
	v_exp_f32_e32 v42, v42
	v_exp_f32_e32 v43, v43
	v_fma_f32 v54, v54, v244, v238
	v_fma_f32 v55, v55, v244, v239
	v_pk_add_f32 v[70:71], v[30:31], v[70:71]
	v_exp_f32_e32 v46, v46
	v_exp_f32_e32 v47, v47
	v_fma_f32 v58, v58, v244, v238
	v_fma_f32 v59, v59, v244, v239
	v_pk_add_f32 v[70:71], v[34:35], v[70:71]
	v_exp_f32_e32 v50, v50
	v_exp_f32_e32 v51, v51
	v_fma_f32 v62, v62, v244, v238
	v_fma_f32 v63, v63, v244, v239
	v_pk_add_f32 v[70:71], v[38:39], v[70:71]
	v_exp_f32_e32 v54, v54
	v_exp_f32_e32 v55, v55
	v_exp_f32_e32 v58, v58
	v_exp_f32_e32 v59, v59
	s_waitcnt lgkmcnt(0)
	v_pk_add_f32 v[64:65], v[64:65], v[72:73]
	v_pk_add_f32 v[70:71], v[42:43], v[70:71]
	v_exp_f32_e32 v62, v62
	v_exp_f32_e32 v63, v63
	s_nop 1
	v_mov_b32_dpp v72, v64 row_ror:4 row_mask:0xf bank_mask:0xf
	s_nop 1
	v_mov_b32_dpp v73, v65 row_ror:4 row_mask:0xf bank_mask:0xf
	v_pk_add_f32 v[70:71], v[46:47], v[70:71]
	s_waitcnt lgkmcnt(0)
	v_pk_add_f32 v[64:65], v[64:65], v[72:73]
	v_pk_add_f32 v[70:71], v[50:51], v[70:71]
	s_nop 0
	v_pk_add_f32 v[70:71], v[54:55], v[70:71]
	s_nop 0
	v_pk_add_f32 v[70:71], v[58:59], v[70:71]
	s_nop 0
	v_pk_add_f32 v[70:71], v[62:63], v[70:71]
	s_nop 1
	v_mov_b32_dpp v72, v70 quad_perm:[1,0,3,2] row_mask:0xf bank_mask:0xf
	s_nop 1
	v_mov_b32_dpp v73, v71 quad_perm:[1,0,3,2] row_mask:0xf bank_mask:0xf
	s_waitcnt lgkmcnt(0)
	v_pk_add_f32 v[70:71], v[70:71], v[72:73]
	s_nop 1
	v_mov_b32_dpp v66, v70 quad_perm:[2,3,0,1] row_mask:0xf bank_mask:0xf
	s_nop 1
	v_mov_b32_dpp v67, v71 quad_perm:[2,3,0,1] row_mask:0xf bank_mask:0xf
	s_waitcnt lgkmcnt(0)
	v_pk_add_f32 v[66:67], v[70:71], v[66:67]
	s_nop 1
	v_mov_b32_dpp v70, v66 row_ror:4 row_mask:0xf bank_mask:0xf
	s_nop 1
	v_mov_b32_dpp v71, v67 row_ror:4 row_mask:0xf bank_mask:0xf
	s_waitcnt lgkmcnt(0)
	v_pk_add_f32 v[68:69], v[66:67], v[70:71]
	s_nop 1
	v_mov_b32_dpp v66, v64 row_ror:8 row_mask:0xf bank_mask:0xf
	s_nop 1
	v_mov_b32_dpp v67, v65 row_ror:8 row_mask:0xf bank_mask:0xf
	s_nop 1
	v_mov_b32_dpp v70, v68 row_ror:8 row_mask:0xf bank_mask:0xf
	s_nop 1
	v_mov_b32_dpp v71, v69 row_ror:8 row_mask:0xf bank_mask:0xf
	s_and_saveexec_b64 s[50:51], s[46:47]
	s_cbranch_execz .LBB0_848
	s_waitcnt lgkmcnt(2)
	v_pk_add_f32 v[64:65], v[64:65], v[66:67]
	s_waitcnt lgkmcnt(0)
	v_pk_add_f32 v[68:69], v[68:69], v[70:71]
	v_div_scale_f32 v66, s[60:61], v65, v65, 1.0
	v_rcp_f32_e32 v67, v66
	s_nop 0
	v_fma_f32 v70, -v66, v67, 1.0
	v_fmac_f32_e32 v67, v70, v67
	v_div_scale_f32 v70, vcc, 1.0, v65, 1.0
	v_mul_f32_e32 v71, v70, v67
	v_fma_f32 v72, -v66, v71, v70
	v_fmac_f32_e32 v71, v72, v67
	v_fma_f32 v66, -v66, v71, v70
	v_div_fmas_f32 v66, v66, v67, v71
	v_div_fixup_f32 v71, v66, v65, 1.0
	v_div_scale_f32 v65, s[60:61], v64, v64, 1.0
	v_rcp_f32_e32 v66, v65
	s_nop 0
	v_fma_f32 v67, -v65, v66, 1.0
	v_fmac_f32_e32 v66, v67, v66
	v_div_scale_f32 v67, vcc, 1.0, v64, 1.0
	v_mul_f32_e32 v70, v67, v66
	v_fma_f32 v72, -v65, v70, v67
	v_fmac_f32_e32 v70, v72, v66
	v_fma_f32 v65, -v65, v70, v67
	v_div_fmas_f32 v65, v65, v66, v70
	v_div_fixup_f32 v70, v65, v64, 1.0
	v_div_scale_f32 v64, s[60:61], v69, v69, 1.0
	v_rcp_f32_e32 v65, v64
	v_pk_mul_f32 v[2:3], v[2:3], v[70:71]
	v_fma_f32 v66, -v64, v65, 1.0
	v_fmac_f32_e32 v65, v66, v65
	v_div_scale_f32 v66, vcc, 1.0, v69, 1.0
	v_mul_f32_e32 v67, v66, v65
	v_fma_f32 v72, -v64, v67, v66
	v_fmac_f32_e32 v67, v72, v65
	v_fma_f32 v64, -v64, v67, v66
	v_div_fmas_f32 v64, v64, v65, v67
	v_div_fixup_f32 v69, v64, v69, 1.0
	v_div_scale_f32 v64, s[60:61], v68, v68, 1.0
	v_rcp_f32_e32 v65, v64
	s_nop 0
	v_fma_f32 v66, -v64, v65, 1.0
	v_fmac_f32_e32 v65, v66, v65
	v_div_scale_f32 v66, vcc, 1.0, v68, 1.0
	v_mul_f32_e32 v67, v66, v65
	v_fma_f32 v72, -v64, v67, v66
	v_fmac_f32_e32 v67, v72, v65
	v_fma_f32 v64, -v64, v67, v66
	v_div_fmas_f32 v64, v64, v65, v67
	v_div_fixup_f32 v68, v64, v68, 1.0
	v_pk_mul_f32 v[66:67], v[4:5], v[68:69]
	v_pk_mul_f32 v[4:5], v[6:7], v[68:69]
	v_pk_mul_f32 v[64:65], v[0:1], v[70:71]
	ds_write_b128 v210, v[2:5] offset:256
	v_pk_mul_f32 v[2:3], v[10:11], v[68:69]
	v_pk_mul_f32 v[0:1], v[8:9], v[70:71]
	ds_write_b128 v210, v[0:3] offset:512
	v_pk_mul_f32 v[2:3], v[14:15], v[68:69]
	v_pk_mul_f32 v[0:1], v[12:13], v[70:71]
	ds_write_b128 v210, v[0:3] offset:768
	v_pk_mul_f32 v[2:3], v[18:19], v[68:69]
	v_pk_mul_f32 v[0:1], v[16:17], v[70:71]
	ds_write_b128 v210, v[0:3] offset:1024
	v_pk_mul_f32 v[2:3], v[22:23], v[68:69]
	v_pk_mul_f32 v[0:1], v[20:21], v[70:71]
	ds_write_b128 v210, v[0:3] offset:1280
	v_pk_mul_f32 v[2:3], v[26:27], v[68:69]
	v_pk_mul_f32 v[0:1], v[24:25], v[70:71]
	ds_write_b128 v210, v[0:3] offset:1536
	v_pk_mul_f32 v[2:3], v[30:31], v[68:69]
	v_pk_mul_f32 v[0:1], v[28:29], v[70:71]
	ds_write_b128 v210, v[0:3] offset:1792
	v_pk_mul_f32 v[2:3], v[34:35], v[68:69]
	v_pk_mul_f32 v[0:1], v[32:33], v[70:71]
	ds_write_b128 v210, v[0:3] offset:2048
	v_pk_mul_f32 v[2:3], v[38:39], v[68:69]
	v_pk_mul_f32 v[0:1], v[36:37], v[70:71]
	ds_write_b128 v210, v[0:3] offset:2304
	v_pk_mul_f32 v[2:3], v[42:43], v[68:69]
	v_pk_mul_f32 v[0:1], v[40:41], v[70:71]
	ds_write_b128 v210, v[0:3] offset:2560
	v_pk_mul_f32 v[2:3], v[46:47], v[68:69]
	v_pk_mul_f32 v[0:1], v[44:45], v[70:71]
	ds_write_b128 v210, v[0:3] offset:2816
	v_pk_mul_f32 v[2:3], v[50:51], v[68:69]
	v_pk_mul_f32 v[0:1], v[48:49], v[70:71]
	ds_write_b128 v210, v[0:3] offset:3072
	v_pk_mul_f32 v[2:3], v[54:55], v[68:69]
	v_pk_mul_f32 v[0:1], v[52:53], v[70:71]
	ds_write_b128 v210, v[0:3] offset:3328
	v_pk_mul_f32 v[2:3], v[58:59], v[68:69]
	v_pk_mul_f32 v[0:1], v[56:57], v[70:71]
	ds_write_b128 v210, v[0:3] offset:3584
	v_pk_mul_f32 v[2:3], v[62:63], v[68:69]
	v_pk_mul_f32 v[0:1], v[60:61], v[70:71]
	ds_write_b128 v210, v[64:67]
	ds_write_b128 v210, v[0:3] offset:3840
